# GEMM back-edge rotation: load phase first, falls through into the barrier+MFMA segment; loop back edge is the conditional branch after the closing barrier; later code kept at its previous placement
# speedup vs baseline: 1.0033x; 1.0033x over previous
; #define STAGE_ALL(bufi, kt) do { STAGEA(SA(bufi, 0), brow, kt); STAGEA(SA(bufi, 1), brow + HALF, kt); STAGEB(SB(bufi), bcol, kt); } while (0)
; #define WAIT_V(n) asm volatile("s_waitcnt vmcnt(" #n ")" ::: "memory")
; #define BAR __builtin_amdgcn_s_barrier()
;     ...
;   const int wid = tid >> 6, lane = tid & 63, wr = wid >> 1, wc = wid & 1, fr = lane & 15, fq = lane >> 4;
;   acc_t acc;
; #pragma unroll
;   for (int m = 0; m < 4; ++m)
; #pragma unroll
;     for (int n = 0; n < 4; ++n) acc[m][n] = f32x4{0.f, 0.f, 0.f, 0.f};
;   const int nt = K / BK;
;   unsigned oA0, oA1, oB0, oB1;
;   { int _r, _c; stage_rc(tid * 16, _r, _c); oA0 = _r * lda + _c; oB0 = _r * ldb + _c;
;     stage_rc(tid * 16 + 8192, _r, _c); oA1 = _r * lda + _c; oB1 = _r * ldb + _c; }
;   if (!preloaded) {
;     STAGE_ALL(0, 0);
;     if (nt > 1) STAGE_ALL(1, 1);
;   }
;     ...
;     for (int t = 0; t < nt; ++t) {
;       const char* pa = (const char*)SA(b, wr >> 1);
;       const char* pb = (const char*)SB(b);
;       bf16x8 At[4][2], Bf[4][2];
; #pragma unroll
;       for (int m = 0; m < 4; ++m)
; #pragma unroll
;         for (int k = 0; k < 2; ++k) At[m][k] = *reinterpret_cast<const bf16x8*>(pa + lds_byte((wr & 1) * 64 + m * 16 + fr, k * 32 + fq * 8));
; #pragma unroll
;       for (int n = 0; n < 4; ++n)
; #pragma unroll
;         for (int k = 0; k < 2; ++k) Bf[n][k] = *reinterpret_cast<const bf16x8*>(pb + lds_byte(wc * 64 + n * 16 + fr, k * 32 + fq * 8));
;       if (t + 2 < nt) { const int b2 = (b == 0) ? 2 : b - 1; STAGE_ALL(b2, t + 2); WAIT_V(6); } else { WAIT_V(0); }
;       asm volatile("s_waitcnt lgkmcnt(0)" ::: "memory");
;       __builtin_amdgcn_sched_barrier(0);
;       BAR;
.LBB0_40:
	s_or_b64 exec, exec, s[10:11]
	v_and_b32_e32 v8, 15, v133
	v_and_b32_e32 v9, 48, v133
	v_lshl_or_b32 v8, v8, 6, v9
	v_lshlrev_b32_e32 v9, 2, v133
	v_and_b32_e32 v9, 32, v9
	v_xad_u32 v8, v8, v9, 16
	v_lshlrev_b32_e32 v9, 6, v133
	v_lshlrev_b32_e32 v10, 7, v133
	v_and_b32_e32 v9, 0x2000, v9
	v_and_b32_e32 v10, 0x2000, v10
	v_add_u32_e32 v129, v8, v9
	v_add_u32_e32 v131, v8, v10
	v_lshrrev_b32_e32 v8, 1, v4
	v_mul_lo_u32 v4, v6, s66
	s_mov_b32 s61, 0xb000
	v_mad_u64_u32 v[8:9], s[10:11], v8, s61, v[4:5]
	v_or_b32_e32 v4, v8, v5
	s_add_u32 s10, s47, s41
	v_lshrrev_b32_e32 v6, 1, v0
	v_mul_lo_u32 v0, v2, s66
	v_add_u32_sdwa v196, v4, sext(v7) dst_sel:DWORD dst_unused:UNUSED_PAD src0_sel:DWORD src1_sel:WORD_0
	s_addc_u32 s11, s48, s40
	v_mad_u64_u32 v[6:7], s[40:41], v6, s61, v[0:1]
	v_or_b32_e32 v0, v6, v1
	v_lshlrev_b64 v[4:5], 1, v[196:197]
	v_add_u32_sdwa v196, v0, sext(v3) dst_sel:DWORD dst_unused:UNUSED_PAD src0_sel:DWORD src1_sel:WORD_0
	v_lshlrev_b64 v[0:1], 1, v[196:197]
	v_lshl_add_u64 v[134:135], s[10:11], 0, v[4:5]
	v_lshl_add_u64 v[136:137], s[10:11], 0, v[0:1]
	s_add_u32 s10, s54, s37
	s_addc_u32 s11, s55, s36
	v_mov_b32_e32 v60, 0
	v_ashrrev_i32_e32 v132, 8, v133
	v_lshl_add_u64 v[138:139], s[10:11], 0, v[4:5]
	v_lshl_add_u64 v[140:141], s[10:11], 0, v[0:1]
	s_mov_b32 s61, 0
	s_mov_b64 s[10:11], 0
	s_mov_b32 s62, 0
	v_mov_b32_e32 v61, v60
	v_mov_b32_e32 v62, v60
	v_mov_b32_e32 v63, v60
	v_mov_b32_e32 v56, v60
	v_mov_b32_e32 v57, v60
	v_mov_b32_e32 v58, v60
	v_mov_b32_e32 v59, v60
	v_mov_b32_e32 v52, v60
	v_mov_b32_e32 v53, v60
	v_mov_b32_e32 v54, v60
	v_mov_b32_e32 v55, v60
	v_mov_b32_e32 v48, v60
	v_mov_b32_e32 v49, v60
	v_mov_b32_e32 v50, v60
	v_mov_b32_e32 v51, v60
	v_mov_b32_e32 v44, v60
	v_mov_b32_e32 v45, v60
	v_mov_b32_e32 v46, v60
	v_mov_b32_e32 v47, v60
	v_mov_b32_e32 v40, v60
	v_mov_b32_e32 v41, v60
	v_mov_b32_e32 v42, v60
	v_mov_b32_e32 v43, v60
	v_mov_b32_e32 v36, v60
	v_mov_b32_e32 v37, v60
	v_mov_b32_e32 v38, v60
	v_mov_b32_e32 v39, v60
	v_mov_b32_e32 v32, v60
	v_mov_b32_e32 v33, v60
	v_mov_b32_e32 v34, v60
	v_mov_b32_e32 v35, v60
	v_mov_b32_e32 v28, v60
	v_mov_b32_e32 v29, v60
	v_mov_b32_e32 v30, v60
	v_mov_b32_e32 v31, v60
	v_mov_b32_e32 v24, v60
	v_mov_b32_e32 v25, v60
	v_mov_b32_e32 v26, v60
	v_mov_b32_e32 v27, v60
	v_mov_b32_e32 v20, v60
	v_mov_b32_e32 v21, v60
	v_mov_b32_e32 v22, v60
	v_mov_b32_e32 v23, v60
	v_mov_b32_e32 v16, v60
	v_mov_b32_e32 v17, v60
	v_mov_b32_e32 v18, v60
	v_mov_b32_e32 v19, v60
	v_mov_b32_e32 v12, v60
	v_mov_b32_e32 v13, v60
	v_mov_b32_e32 v14, v60
	v_mov_b32_e32 v15, v60
	v_mov_b32_e32 v8, v60
	v_mov_b32_e32 v9, v60
	v_mov_b32_e32 v10, v60
	v_mov_b32_e32 v11, v60
	v_mov_b32_e32 v4, v60
	v_mov_b32_e32 v5, v60
	v_mov_b32_e32 v6, v60
	v_mov_b32_e32 v7, v60
	v_mov_b32_e32 v0, v60
	v_mov_b32_e32 v1, v60
	v_mov_b32_e32 v2, v60
	v_mov_b32_e32 v3, v60
	v_readfirstlane_b32 s99, v151
	v_lshl_add_u32 v174, v132, 14, v129
	v_mov_b32_e32 v161, v131
	v_lshl_add_u64 v[162:163], v[140:141], 0, s[16:17]
	v_lshl_add_u64 v[164:165], v[138:139], 0, s[16:17]
	v_lshl_add_u64 v[166:167], v[140:141], 0, s[18:19]
	v_lshl_add_u64 v[168:169], v[138:139], 0, s[18:19]
	v_mov_b64_e32 v[170:171], v[136:137]
	v_mov_b64_e32 v[172:173], v[134:135]
	v_mov_b32_e32 v160, v174
	s_add_u32 s98, s99, 0x18000
	s_nop 0
.LBB0_42:
	ds_read_b128 v[108:111], v160
	ds_read_b128 v[76:79], v160 offset:1024
	ds_read_b128 v[104:107], v160 offset:2048
	ds_read_b128 v[72:75], v160 offset:3072
	ds_read_b128 v[100:103], v160 offset:4096
	ds_read_b128 v[68:71], v160 offset:5120
	ds_read_b128 v[96:99], v160 offset:6144
	ds_read_b128 v[64:67], v160 offset:7168
	ds_read_b128 v[112:115], v161 offset:32768
	ds_read_b128 v[80:83], v161 offset:33792
	ds_read_b128 v[116:119], v161 offset:34816
	ds_read_b128 v[84:87], v161 offset:35840
	ds_read_b128 v[120:123], v161 offset:36864
	ds_read_b128 v[88:91], v161 offset:37888
	ds_read_b128 v[124:127], v161 offset:38912
	ds_read_b128 v[92:95], v161 offset:39936
	s_cmp_gt_u32 s62, 41
	s_cbranch_scc1 .Lgc1_nostage
	s_mov_b32 m0, s98
	s_nop 0
	global_load_lds_dwordx4 v[162:163], off
	s_add_u32 m0, s98, 0x2000
	s_nop 0
	global_load_lds_dwordx4 v[164:165], off
	s_add_u32 m0, s98, 0x4000
	s_nop 0
	global_load_lds_dwordx4 v[166:167], off
	s_waitcnt vmcnt(3)
.LBB0_41:
	s_waitcnt lgkmcnt(0)
	s_barrier
	s_setprio 1
	s_waitcnt lgkmcnt(0)
	v_mfma_f32_16x16x32_bf16 v[60:63], v[112:115], v[108:111], v[60:63]
	v_mfma_f32_16x16x32_bf16 v[56:59], v[116:119], v[108:111], v[56:59]
	s_cmp_gt_u32 s62, 41
	s_cbranch_scc1 .Lgc1_skd3
	s_add_u32 m0, s98, 0x6000
	s_nop 0
	global_load_lds_dwordx4 v[168:169], off

; #define STAGE_ALL(bufi, kt) do { STAGEA(SA(bufi, 0), brow, kt); STAGEA(SA(bufi, 1), brow + HALF, kt); STAGEB(SB(bufi), bcol, kt); } while (0)
; #define WAIT_V(n) asm volatile("s_waitcnt vmcnt(" #n ")" ::: "memory")
; #define BAR __builtin_amdgcn_s_barrier()
;     ...
;       if (t + 2 < nt) { const int b2 = (b == 0) ? 2 : b - 1; STAGE_ALL(b2, t + 2); WAIT_V(6); } else { WAIT_V(0); }
;       asm volatile("s_waitcnt lgkmcnt(0)" ::: "memory");
;       __builtin_amdgcn_sched_barrier(0);
;       BAR;
;       __builtin_amdgcn_sched_barrier(0);
;       __builtin_amdgcn_s_setprio(1);
; #pragma unroll
;       for (int k = 0; k < 2; ++k)
; #pragma unroll
;         for (int m = 0; m < 4; ++m)
; #pragma unroll
;           for (int n = 0; n < 4; ++n) acc[m][n] = __builtin_amdgcn_mfma_f32_16x16x32_bf16(Bf[n][k], At[m][k], acc[m][n], 0, 0, 0);
;       __builtin_amdgcn_s_setprio(0);
;       __builtin_amdgcn_sched_barrier(0);
;       BAR;
;       __builtin_amdgcn_sched_barrier(0);
;       b = (b == 2) ? 0 : b + 1;
.Lgc1_skd5:
	v_mfma_f32_16x16x32_bf16 v[20:23], v[120:123], v[100:103], v[20:23]
	v_mfma_f32_16x16x32_bf16 v[16:19], v[124:127], v[100:103], v[16:19]
	v_mfma_f32_16x16x32_bf16 v[12:15], v[112:115], v[96:99], v[12:15]
	s_add_i32 s36, s61, 1
	s_cmp_lg_u32 s61, 2
	s_cselect_b32 s61, s36, 0
	s_add_i32 s62, s62, 1
	s_add_u32 s10, s10, 0x80
	s_addc_u32 s11, s11, 0
	s_mul_i32 s36, s61, 0xc000
	s_mul_i32 s98, s61, 0x6000
	s_addk_i32 s98, 0xa000
	s_cmp_lg_u32 s61, 0
	s_cselect_b32 s98, s98, 0xc000
	s_lshl_b32 s98, s98, 1
	s_add_u32 s98, s98, s99
	v_mfma_f32_16x16x32_bf16 v[8:11], v[116:119], v[96:99], v[8:11]
	v_mfma_f32_16x16x32_bf16 v[4:7], v[120:123], v[96:99], v[4:7]
	v_add_u32_e32 v160, s36, v174
	v_mfma_f32_16x16x32_bf16 v[0:3], v[124:127], v[96:99], v[0:3]
	v_mfma_f32_16x16x32_bf16 v[60:63], v[80:83], v[76:79], v[60:63]
	v_add_u32_e32 v161, s36, v131
	v_mfma_f32_16x16x32_bf16 v[56:59], v[84:87], v[76:79], v[56:59]
	v_mfma_f32_16x16x32_bf16 v[52:55], v[88:91], v[76:79], v[52:55]
	v_lshl_add_u64 v[162:163], v[162:163], 0, s[14:15]
	v_mfma_f32_16x16x32_bf16 v[48:51], v[92:95], v[76:79], v[48:51]
	v_mfma_f32_16x16x32_bf16 v[44:47], v[80:83], v[72:75], v[44:47]
	v_lshl_add_u64 v[164:165], v[164:165], 0, s[14:15]
	v_mfma_f32_16x16x32_bf16 v[40:43], v[84:87], v[72:75], v[40:43]
	v_mfma_f32_16x16x32_bf16 v[36:39], v[88:91], v[72:75], v[36:39]
	v_lshl_add_u64 v[166:167], v[166:167], 0, s[14:15]
	v_mfma_f32_16x16x32_bf16 v[32:35], v[92:95], v[72:75], v[32:35]
	v_mfma_f32_16x16x32_bf16 v[28:31], v[80:83], v[68:71], v[28:31]
	v_lshl_add_u64 v[168:169], v[168:169], 0, s[14:15]
	v_mfma_f32_16x16x32_bf16 v[24:27], v[84:87], v[68:71], v[24:27]
	v_mfma_f32_16x16x32_bf16 v[20:23], v[88:91], v[68:71], v[20:23]
	v_lshl_add_u64 v[170:171], v[170:171], 0, s[14:15]
	v_mfma_f32_16x16x32_bf16 v[16:19], v[92:95], v[68:71], v[16:19]
	v_mfma_f32_16x16x32_bf16 v[12:15], v[80:83], v[64:67], v[12:15]
	v_lshl_add_u64 v[172:173], v[172:173], 0, s[14:15]
	v_mfma_f32_16x16x32_bf16 v[8:11], v[84:87], v[64:67], v[8:11]
	v_mfma_f32_16x16x32_bf16 v[4:7], v[88:91], v[64:67], v[4:7]
	v_mfma_f32_16x16x32_bf16 v[0:3], v[92:95], v[64:67], v[0:3]
	s_setprio 0
	s_barrier
	s_cmpk_eq_i32 s10, 0x1600
	s_cbranch_scc0 .LBB0_42
	s_branch .LBB0_46

; #define STAGE_ALL(bufi, kt) do { STAGEA(SA(bufi, 0), brow, kt); STAGEA(SA(bufi, 1), brow + HALF, kt); STAGEB(SB(bufi), bcol, kt); } while (0)
; #define WAIT_V(n) asm volatile("s_waitcnt vmcnt(" #n ")" ::: "memory")
; #define BAR __builtin_amdgcn_s_barrier()
;     ...
;   const int wid = tid >> 6, lane = tid & 63, wr = wid >> 1, wc = wid & 1, fr = lane & 15, fq = lane >> 4;
;   acc_t acc;
; #pragma unroll
;   for (int m = 0; m < 4; ++m)
; #pragma unroll
;     for (int n = 0; n < 4; ++n) acc[m][n] = f32x4{0.f, 0.f, 0.f, 0.f};
;   const int nt = K / BK;
;   unsigned oA0, oA1, oB0, oB1;
;   { int _r, _c; stage_rc(tid * 16, _r, _c); oA0 = _r * lda + _c; oB0 = _r * ldb + _c;
;     stage_rc(tid * 16 + 8192, _r, _c); oA1 = _r * lda + _c; oB1 = _r * ldb + _c; }
;   if (!preloaded) {
;     STAGE_ALL(0, 0);
;     if (nt > 1) STAGE_ALL(1, 1);
;   }
;     ...
;     for (int t = 0; t < nt; ++t) {
;       const char* pa = (const char*)SA(b, wr >> 1);
;       const char* pb = (const char*)SB(b);
;       bf16x8 At[4][2], Bf[4][2];
; #pragma unroll
;       for (int m = 0; m < 4; ++m)
; #pragma unroll
;         for (int k = 0; k < 2; ++k) At[m][k] = *reinterpret_cast<const bf16x8*>(pa + lds_byte((wr & 1) * 64 + m * 16 + fr, k * 32 + fq * 8));
; #pragma unroll
;       for (int n = 0; n < 4; ++n)
; #pragma unroll
;         for (int k = 0; k < 2; ++k) Bf[n][k] = *reinterpret_cast<const bf16x8*>(pb + lds_byte(wc * 64 + n * 16 + fr, k * 32 + fq * 8));
;       if (t + 2 < nt) { const int b2 = (b == 0) ? 2 : b - 1; STAGE_ALL(b2, t + 2); WAIT_V(6); } else { WAIT_V(0); }
;       asm volatile("s_waitcnt lgkmcnt(0)" ::: "memory");
;       __builtin_amdgcn_sched_barrier(0);
;       BAR;
.LBB0_72:
	s_or_b64 exec, exec, s[44:45]
	v_lshlrev_b32_e32 v4, 13, v4
	v_and_b32_e32 v4, 0xffffc000, v4
	v_lshlrev_b32_e32 v0, 13, v0
	v_lshl_add_u32 v4, v5, 10, v4
	v_and_b32_e32 v0, 0xffffc000, v0
	s_ashr_i32 s43, s42, 31
	s_ashr_i32 s11, s10, 31
	v_or_b32_e32 v4, v4, v6
	v_lshl_add_u32 v0, v1, 10, v0
	v_and_b32_e32 v8, 15, v133
	v_and_b32_e32 v9, 48, v133
	s_lshl_b64 s[36:37], s[42:43], 11
	s_lshl_b64 s[10:11], s[10:11], 11
	v_add_u32_sdwa v196, v4, sext(v7) dst_sel:DWORD dst_unused:UNUSED_PAD src0_sel:DWORD src1_sel:WORD_0
	v_or_b32_e32 v0, v0, v2
	v_lshl_or_b32 v8, v8, 6, v9
	v_lshlrev_b32_e32 v9, 2, v133
	v_lshlrev_b64 v[4:5], 1, v[196:197]
	s_add_u32 s10, s51, s10
	v_add_u32_sdwa v196, v0, sext(v3) dst_sel:DWORD dst_unused:UNUSED_PAD src0_sel:DWORD src1_sel:WORD_0
	v_and_b32_e32 v9, 32, v9
	s_addc_u32 s11, s58, s11
	v_lshlrev_b64 v[0:1], 1, v[196:197]
	v_xad_u32 v8, v8, v9, 16
	v_lshlrev_b32_e32 v9, 6, v133
	v_lshlrev_b32_e32 v10, 7, v133
	v_lshl_add_u64 v[134:135], s[10:11], 0, v[4:5]
	v_lshl_add_u64 v[136:137], s[10:11], 0, v[0:1]
	s_add_u32 s10, s54, s36
	v_and_b32_e32 v9, 0x2000, v9
	v_and_b32_e32 v10, 0x2000, v10
	s_addc_u32 s11, s55, s37
	v_mov_b32_e32 v56, 0
	v_ashrrev_i32_e32 v132, 8, v133
	v_add_u32_e32 v129, v8, v9
	v_add_u32_e32 v131, v8, v10
	v_lshl_add_u64 v[138:139], s[10:11], 0, v[4:5]
	v_lshl_add_u64 v[140:141], s[10:11], 0, v[0:1]
	s_mov_b32 s43, 0
	s_mov_b64 s[10:11], 0
	s_mov_b32 s64, 0
	v_mov_b32_e32 v57, v56
	v_mov_b32_e32 v58, v56
	v_mov_b32_e32 v59, v56
	v_mov_b32_e32 v48, v56
	v_mov_b32_e32 v49, v56
	v_mov_b32_e32 v50, v56
	v_mov_b32_e32 v51, v56
	v_mov_b32_e32 v60, v56
	v_mov_b32_e32 v61, v56
	v_mov_b32_e32 v62, v56
	v_mov_b32_e32 v63, v56
	v_mov_b32_e32 v52, v56
	v_mov_b32_e32 v53, v56
	v_mov_b32_e32 v54, v56
	v_mov_b32_e32 v55, v56
	v_mov_b32_e32 v40, v56
	v_mov_b32_e32 v41, v56
	v_mov_b32_e32 v42, v56
	v_mov_b32_e32 v43, v56
	v_mov_b32_e32 v32, v56
	v_mov_b32_e32 v33, v56
	v_mov_b32_e32 v34, v56
	v_mov_b32_e32 v35, v56
	v_mov_b32_e32 v44, v56
	v_mov_b32_e32 v45, v56
	v_mov_b32_e32 v46, v56
	v_mov_b32_e32 v47, v56
	v_mov_b32_e32 v36, v56
	v_mov_b32_e32 v37, v56
	v_mov_b32_e32 v38, v56
	v_mov_b32_e32 v39, v56
	v_mov_b32_e32 v24, v56
	v_mov_b32_e32 v25, v56
	v_mov_b32_e32 v26, v56
	v_mov_b32_e32 v27, v56
	v_mov_b32_e32 v16, v56
	v_mov_b32_e32 v17, v56
	v_mov_b32_e32 v18, v56
	v_mov_b32_e32 v19, v56
	v_mov_b32_e32 v28, v56
	v_mov_b32_e32 v29, v56
	v_mov_b32_e32 v30, v56
	v_mov_b32_e32 v31, v56
	v_mov_b32_e32 v20, v56
	v_mov_b32_e32 v21, v56
	v_mov_b32_e32 v22, v56
	v_mov_b32_e32 v23, v56
	v_mov_b32_e32 v8, v56
	v_mov_b32_e32 v9, v56
	v_mov_b32_e32 v10, v56
	v_mov_b32_e32 v11, v56
	v_mov_b32_e32 v0, v56
	v_mov_b32_e32 v1, v56
	v_mov_b32_e32 v2, v56
	v_mov_b32_e32 v3, v56
	v_mov_b32_e32 v12, v56
	v_mov_b32_e32 v13, v56
	v_mov_b32_e32 v14, v56
	v_mov_b32_e32 v15, v56
	v_mov_b32_e32 v4, v56
	v_mov_b32_e32 v5, v56
	v_mov_b32_e32 v6, v56
	v_mov_b32_e32 v7, v56
	v_readfirstlane_b32 s99, v151
	v_lshl_add_u32 v174, v132, 14, v129
	v_mov_b32_e32 v161, v131
	v_lshl_add_u64 v[162:163], v[140:141], 0, s[20:21]
	v_lshl_add_u64 v[164:165], v[138:139], 0, s[20:21]
	v_lshl_add_u64 v[166:167], v[140:141], 0, s[22:23]
	v_lshl_add_u64 v[168:169], v[138:139], 0, s[22:23]
	v_mov_b64_e32 v[170:171], v[136:137]
	v_mov_b64_e32 v[172:173], v[134:135]
	v_mov_b32_e32 v160, v174
	s_add_u32 s98, s99, 0x18000
	s_nop 0
.LBB0_74:
	ds_read_b128 v[108:111], v160
	ds_read_b128 v[76:79], v160 offset:1024
	ds_read_b128 v[104:107], v160 offset:2048
	ds_read_b128 v[72:75], v160 offset:3072
	ds_read_b128 v[100:103], v160 offset:4096
	ds_read_b128 v[68:71], v160 offset:5120
	ds_read_b128 v[96:99], v160 offset:6144
	ds_read_b128 v[64:67], v160 offset:7168
	ds_read_b128 v[112:115], v161 offset:32768
	ds_read_b128 v[80:83], v161 offset:33792
	ds_read_b128 v[116:119], v161 offset:34816
	ds_read_b128 v[84:87], v161 offset:35840
	ds_read_b128 v[120:123], v161 offset:36864
	ds_read_b128 v[88:91], v161 offset:37888
	ds_read_b128 v[124:127], v161 offset:38912
	ds_read_b128 v[92:95], v161 offset:39936
	s_cmp_gt_u32 s64, 13
	s_cbranch_scc1 .Lgc2_nostage
	s_mov_b32 m0, s98
	s_nop 0
	global_load_lds_dwordx4 v[162:163], off
	s_add_u32 m0, s98, 0x2000
	s_nop 0
	global_load_lds_dwordx4 v[164:165], off
	s_add_u32 m0, s98, 0x4000
	s_nop 0
	global_load_lds_dwordx4 v[166:167], off
	s_waitcnt vmcnt(3)
.LBB0_73:
	s_waitcnt lgkmcnt(0)
	s_barrier
	s_setprio 1
	s_waitcnt lgkmcnt(0)
	v_mfma_f32_16x16x32_bf16 v[56:59], v[112:115], v[108:111], v[56:59]
	v_mfma_f32_16x16x32_bf16 v[48:51], v[116:119], v[108:111], v[48:51]
	s_cmp_gt_u32 s64, 13
	s_cbranch_scc1 .Lgc2_skd3
	s_add_u32 m0, s98, 0x6000
	s_nop 0
	global_load_lds_dwordx4 v[168:169], off

; #define STAGE_ALL(bufi, kt) do { STAGEA(SA(bufi, 0), brow, kt); STAGEA(SA(bufi, 1), brow + HALF, kt); STAGEB(SB(bufi), bcol, kt); } while (0)
; #define WAIT_V(n) asm volatile("s_waitcnt vmcnt(" #n ")" ::: "memory")
; #define BAR __builtin_amdgcn_s_barrier()
;     ...
;       if (t + 2 < nt) { const int b2 = (b == 0) ? 2 : b - 1; STAGE_ALL(b2, t + 2); WAIT_V(6); } else { WAIT_V(0); }
;       asm volatile("s_waitcnt lgkmcnt(0)" ::: "memory");
;       __builtin_amdgcn_sched_barrier(0);
;       BAR;
;       __builtin_amdgcn_sched_barrier(0);
;       __builtin_amdgcn_s_setprio(1);
; #pragma unroll
;       for (int k = 0; k < 2; ++k)
; #pragma unroll
;         for (int m = 0; m < 4; ++m)
; #pragma unroll
;           for (int n = 0; n < 4; ++n) acc[m][n] = __builtin_amdgcn_mfma_f32_16x16x32_bf16(Bf[n][k], At[m][k], acc[m][n], 0, 0, 0);
;       __builtin_amdgcn_s_setprio(0);
;       __builtin_amdgcn_sched_barrier(0);
;       BAR;
;       __builtin_amdgcn_sched_barrier(0);
;       b = (b == 2) ? 0 : b + 1;
.Lgc2_skd5:
	v_mfma_f32_16x16x32_bf16 v[28:31], v[120:123], v[100:103], v[28:31]
	v_mfma_f32_16x16x32_bf16 v[20:23], v[124:127], v[100:103], v[20:23]
	v_mfma_f32_16x16x32_bf16 v[8:11], v[112:115], v[96:99], v[8:11]
	s_add_i32 s36, s43, 1
	s_cmp_lg_u32 s43, 2
	s_cselect_b32 s43, s36, 0
	s_add_i32 s64, s64, 1
	s_add_u32 s10, s10, 0x80
	s_addc_u32 s11, s11, 0
	s_mul_i32 s36, s43, 0xc000
	s_mul_i32 s98, s43, 0x6000
	s_addk_i32 s98, 0xa000
	s_cmp_lg_u32 s43, 0
	s_cselect_b32 s98, s98, 0xc000
	s_lshl_b32 s98, s98, 1
	s_add_u32 s98, s98, s99
	v_mfma_f32_16x16x32_bf16 v[0:3], v[116:119], v[96:99], v[0:3]
	v_mfma_f32_16x16x32_bf16 v[12:15], v[120:123], v[96:99], v[12:15]
	v_add_u32_e32 v160, s36, v174
	v_mfma_f32_16x16x32_bf16 v[4:7], v[124:127], v[96:99], v[4:7]
	v_mfma_f32_16x16x32_bf16 v[56:59], v[80:83], v[76:79], v[56:59]
	v_add_u32_e32 v161, s36, v131
	v_mfma_f32_16x16x32_bf16 v[48:51], v[84:87], v[76:79], v[48:51]
	v_mfma_f32_16x16x32_bf16 v[60:63], v[88:91], v[76:79], v[60:63]
	v_lshl_add_u64 v[162:163], v[162:163], 0, s[14:15]
	v_mfma_f32_16x16x32_bf16 v[52:55], v[92:95], v[76:79], v[52:55]
	v_mfma_f32_16x16x32_bf16 v[40:43], v[80:83], v[72:75], v[40:43]
	v_lshl_add_u64 v[164:165], v[164:165], 0, s[14:15]
	v_mfma_f32_16x16x32_bf16 v[32:35], v[84:87], v[72:75], v[32:35]
	v_mfma_f32_16x16x32_bf16 v[44:47], v[88:91], v[72:75], v[44:47]
	v_lshl_add_u64 v[166:167], v[166:167], 0, s[14:15]
	v_mfma_f32_16x16x32_bf16 v[36:39], v[92:95], v[72:75], v[36:39]
	v_mfma_f32_16x16x32_bf16 v[24:27], v[80:83], v[68:71], v[24:27]
	v_lshl_add_u64 v[168:169], v[168:169], 0, s[14:15]
	v_mfma_f32_16x16x32_bf16 v[16:19], v[84:87], v[68:71], v[16:19]
	v_mfma_f32_16x16x32_bf16 v[28:31], v[88:91], v[68:71], v[28:31]
	v_lshl_add_u64 v[170:171], v[170:171], 0, s[14:15]
	v_mfma_f32_16x16x32_bf16 v[20:23], v[92:95], v[68:71], v[20:23]
	v_mfma_f32_16x16x32_bf16 v[8:11], v[80:83], v[64:67], v[8:11]
	v_lshl_add_u64 v[172:173], v[172:173], 0, s[14:15]
	v_mfma_f32_16x16x32_bf16 v[0:3], v[84:87], v[64:67], v[0:3]
	v_mfma_f32_16x16x32_bf16 v[12:15], v[88:91], v[64:67], v[12:15]
	v_mfma_f32_16x16x32_bf16 v[4:7], v[92:95], v[64:67], v[4:7]
	s_setprio 0
	s_barrier
	s_cmpk_eq_i32 s10, 0x800
	s_cbranch_scc0 .LBB0_74
	s_branch .LBB0_78

; #define STAGE_ALL(bufi, kt) do { STAGEA(SA(bufi, 0), brow, kt); STAGEA(SA(bufi, 1), brow + HALF, kt); STAGEB(SB(bufi), bcol, kt); } while (0)
; #define WAIT_V(n) asm volatile("s_waitcnt vmcnt(" #n ")" ::: "memory")
; #define BAR __builtin_amdgcn_s_barrier()
;     ...
;   const int wid = tid >> 6, lane = tid & 63, wr = wid >> 1, wc = wid & 1, fr = lane & 15, fq = lane >> 4;
;   acc_t acc;
; #pragma unroll
;   for (int m = 0; m < 4; ++m)
; #pragma unroll
;     for (int n = 0; n < 4; ++n) acc[m][n] = f32x4{0.f, 0.f, 0.f, 0.f};
;   const int nt = K / BK;
;   unsigned oA0, oA1, oB0, oB1;
;   { int _r, _c; stage_rc(tid * 16, _r, _c); oA0 = _r * lda + _c; oB0 = _r * ldb + _c;
;     stage_rc(tid * 16 + 8192, _r, _c); oA1 = _r * lda + _c; oB1 = _r * ldb + _c; }
;   if (!preloaded) {
;     STAGE_ALL(0, 0);
;     if (nt > 1) STAGE_ALL(1, 1);
;   }
;     ...
;     for (int t = 0; t < nt; ++t) {
;       const char* pa = (const char*)SA(b, wr >> 1);
;       const char* pb = (const char*)SB(b);
;       bf16x8 At[4][2], Bf[4][2];
; #pragma unroll
;       for (int m = 0; m < 4; ++m)
; #pragma unroll
;         for (int k = 0; k < 2; ++k) At[m][k] = *reinterpret_cast<const bf16x8*>(pa + lds_byte((wr & 1) * 64 + m * 16 + fr, k * 32 + fq * 8));
; #pragma unroll
;       for (int n = 0; n < 4; ++n)
; #pragma unroll
;         for (int k = 0; k < 2; ++k) Bf[n][k] = *reinterpret_cast<const bf16x8*>(pb + lds_byte(wc * 64 + n * 16 + fr, k * 32 + fq * 8));
;       if (t + 2 < nt) { const int b2 = (b == 0) ? 2 : b - 1; STAGE_ALL(b2, t + 2); WAIT_V(6); } else { WAIT_V(0); }
;       asm volatile("s_waitcnt lgkmcnt(0)" ::: "memory");
;       __builtin_amdgcn_sched_barrier(0);
;       BAR;
.LBB0_107:
	s_or_b64 exec, exec, s[10:11]
	v_lshlrev_b32_e32 v4, 13, v4
	s_ashr_i32 s41, s40, 31
	s_ashr_i32 s39, s38, 31
	v_and_b32_e32 v4, 0xffffc000, v4
	v_lshlrev_b32_e32 v0, 13, v0
	v_and_b32_e32 v8, 15, v133
	v_and_b32_e32 v9, 48, v133
	s_lshl_b64 s[10:11], s[40:41], 11
	s_lshl_b64 s[36:37], s[38:39], 11
	v_lshl_add_u32 v4, v5, 10, v4
	v_and_b32_e32 v0, 0xffffc000, v0
	v_lshl_or_b32 v8, v8, 6, v9
	v_lshlrev_b32_e32 v9, 2, v133
	v_or_b32_e32 v4, v4, v6
	s_add_u32 s36, s59, s36
	v_lshl_add_u32 v0, v1, 10, v0
	v_and_b32_e32 v9, 32, v9
	v_add_u32_sdwa v196, v4, sext(v7) dst_sel:DWORD dst_unused:UNUSED_PAD src0_sel:DWORD src1_sel:WORD_0
	s_addc_u32 s37, s60, s37
	v_or_b32_e32 v0, v0, v2
	v_xad_u32 v8, v8, v9, 16
	v_lshlrev_b32_e32 v9, 6, v133
	v_lshlrev_b32_e32 v10, 7, v133
	v_lshlrev_b64 v[4:5], 1, v[196:197]
	v_add_u32_sdwa v196, v0, sext(v3) dst_sel:DWORD dst_unused:UNUSED_PAD src0_sel:DWORD src1_sel:WORD_0
	s_add_u32 s10, s54, s10
	v_and_b32_e32 v9, 0x2000, v9
	v_and_b32_e32 v10, 0x2000, v10
	v_lshlrev_b64 v[0:1], 1, v[196:197]
	s_addc_u32 s11, s55, s11
	v_mov_b32_e32 v60, 0
	v_ashrrev_i32_e32 v132, 8, v133
	v_add_u32_e32 v129, v8, v9
	v_add_u32_e32 v131, v8, v10
	v_lshl_add_u64 v[134:135], s[36:37], 0, v[4:5]
	v_lshl_add_u64 v[136:137], s[36:37], 0, v[0:1]
	v_lshl_add_u64 v[138:139], s[10:11], 0, v[4:5]
	v_lshl_add_u64 v[140:141], s[10:11], 0, v[0:1]
	s_mov_b32 s39, 0
	s_mov_b64 s[10:11], 0
	s_mov_b32 s41, 0
	v_mov_b32_e32 v61, v60
	v_mov_b32_e32 v62, v60
	v_mov_b32_e32 v63, v60
	v_mov_b32_e32 v56, v60
	v_mov_b32_e32 v57, v60
	v_mov_b32_e32 v58, v60
	v_mov_b32_e32 v59, v60
	v_mov_b32_e32 v52, v60
	v_mov_b32_e32 v53, v60
	v_mov_b32_e32 v54, v60
	v_mov_b32_e32 v55, v60
	v_mov_b32_e32 v48, v60
	v_mov_b32_e32 v49, v60
	v_mov_b32_e32 v50, v60
	v_mov_b32_e32 v51, v60
	v_mov_b32_e32 v44, v60
	v_mov_b32_e32 v45, v60
	v_mov_b32_e32 v46, v60
	v_mov_b32_e32 v47, v60
	v_mov_b32_e32 v40, v60
	v_mov_b32_e32 v41, v60
	v_mov_b32_e32 v42, v60
	v_mov_b32_e32 v43, v60
	v_mov_b32_e32 v36, v60
	v_mov_b32_e32 v37, v60
	v_mov_b32_e32 v38, v60
	v_mov_b32_e32 v39, v60
	v_mov_b32_e32 v32, v60
	v_mov_b32_e32 v33, v60
	v_mov_b32_e32 v34, v60
	v_mov_b32_e32 v35, v60
	v_mov_b32_e32 v28, v60
	v_mov_b32_e32 v29, v60
	v_mov_b32_e32 v30, v60
	v_mov_b32_e32 v31, v60
	v_mov_b32_e32 v24, v60
	v_mov_b32_e32 v25, v60
	v_mov_b32_e32 v26, v60
	v_mov_b32_e32 v27, v60
	v_mov_b32_e32 v20, v60
	v_mov_b32_e32 v21, v60
	v_mov_b32_e32 v22, v60
	v_mov_b32_e32 v23, v60
	v_mov_b32_e32 v16, v60
	v_mov_b32_e32 v17, v60
	v_mov_b32_e32 v18, v60
	v_mov_b32_e32 v19, v60
	v_mov_b32_e32 v12, v60
	v_mov_b32_e32 v13, v60
	v_mov_b32_e32 v14, v60
	v_mov_b32_e32 v15, v60
	v_mov_b32_e32 v8, v60
	v_mov_b32_e32 v9, v60
	v_mov_b32_e32 v10, v60
	v_mov_b32_e32 v11, v60
	v_mov_b32_e32 v4, v60
	v_mov_b32_e32 v5, v60
	v_mov_b32_e32 v6, v60
	v_mov_b32_e32 v7, v60
	v_mov_b32_e32 v0, v60
	v_mov_b32_e32 v1, v60
	v_mov_b32_e32 v2, v60
	v_mov_b32_e32 v3, v60
	v_readfirstlane_b32 s99, v151
	v_lshl_add_u32 v174, v132, 14, v129
	v_mov_b32_e32 v161, v131
	v_lshl_add_u64 v[162:163], v[140:141], 0, s[24:25]
	v_lshl_add_u64 v[164:165], v[138:139], 0, s[24:25]
	v_lshl_add_u64 v[166:167], v[140:141], 0, s[26:27]
	v_lshl_add_u64 v[168:169], v[138:139], 0, s[26:27]
	v_mov_b64_e32 v[170:171], v[136:137]
	v_mov_b64_e32 v[172:173], v[134:135]
	v_mov_b32_e32 v160, v174
	s_add_u32 s98, s99, 0x18000
	s_nop 0
.LBB0_109:
	ds_read_b128 v[108:111], v160
	ds_read_b128 v[76:79], v160 offset:1024
	ds_read_b128 v[104:107], v160 offset:2048
	ds_read_b128 v[72:75], v160 offset:3072
	ds_read_b128 v[100:103], v160 offset:4096
	ds_read_b128 v[68:71], v160 offset:5120
	ds_read_b128 v[96:99], v160 offset:6144
	ds_read_b128 v[64:67], v160 offset:7168
	ds_read_b128 v[112:115], v161 offset:32768
	ds_read_b128 v[80:83], v161 offset:33792
	ds_read_b128 v[116:119], v161 offset:34816
	ds_read_b128 v[84:87], v161 offset:35840
	ds_read_b128 v[120:123], v161 offset:36864
	ds_read_b128 v[88:91], v161 offset:37888
	ds_read_b128 v[124:127], v161 offset:38912
	ds_read_b128 v[92:95], v161 offset:39936
	s_cmp_gt_u32 s41, 13
	s_cbranch_scc1 .Lgc3_nostage
	s_mov_b32 m0, s98
	s_nop 0
	global_load_lds_dwordx4 v[162:163], off
	s_add_u32 m0, s98, 0x2000
	s_nop 0
	global_load_lds_dwordx4 v[164:165], off
	s_add_u32 m0, s98, 0x4000
	s_nop 0
	global_load_lds_dwordx4 v[166:167], off
	s_waitcnt vmcnt(3)
.LBB0_108:
	s_waitcnt lgkmcnt(0)
	s_barrier
	s_setprio 1
	s_waitcnt lgkmcnt(0)
	v_mfma_f32_16x16x32_bf16 v[60:63], v[112:115], v[108:111], v[60:63]
	v_mfma_f32_16x16x32_bf16 v[56:59], v[116:119], v[108:111], v[56:59]
	s_cmp_gt_u32 s41, 13
	s_cbranch_scc1 .Lgc3_skd3
	s_add_u32 m0, s98, 0x6000
	s_nop 0
	global_load_lds_dwordx4 v[168:169], off

; #define STAGE_ALL(bufi, kt) do { STAGEA(SA(bufi, 0), brow, kt); STAGEA(SA(bufi, 1), brow + HALF, kt); STAGEB(SB(bufi), bcol, kt); } while (0)
; #define WAIT_V(n) asm volatile("s_waitcnt vmcnt(" #n ")" ::: "memory")
; #define BAR __builtin_amdgcn_s_barrier()
;     ...
;       if (t + 2 < nt) { const int b2 = (b == 0) ? 2 : b - 1; STAGE_ALL(b2, t + 2); WAIT_V(6); } else { WAIT_V(0); }
;       asm volatile("s_waitcnt lgkmcnt(0)" ::: "memory");
;       __builtin_amdgcn_sched_barrier(0);
;       BAR;
;       __builtin_amdgcn_sched_barrier(0);
;       __builtin_amdgcn_s_setprio(1);
; #pragma unroll
;       for (int k = 0; k < 2; ++k)
; #pragma unroll
;         for (int m = 0; m < 4; ++m)
; #pragma unroll
;           for (int n = 0; n < 4; ++n) acc[m][n] = __builtin_amdgcn_mfma_f32_16x16x32_bf16(Bf[n][k], At[m][k], acc[m][n], 0, 0, 0);
;       __builtin_amdgcn_s_setprio(0);
;       __builtin_amdgcn_sched_barrier(0);
;       BAR;
;       __builtin_amdgcn_sched_barrier(0);
;       b = (b == 2) ? 0 : b + 1;
.Lgc3_skd5:
	v_mfma_f32_16x16x32_bf16 v[20:23], v[120:123], v[100:103], v[20:23]
	v_mfma_f32_16x16x32_bf16 v[16:19], v[124:127], v[100:103], v[16:19]
	v_mfma_f32_16x16x32_bf16 v[12:15], v[112:115], v[96:99], v[12:15]
	s_add_i32 s36, s39, 1
	s_cmp_lg_u32 s39, 2
	s_cselect_b32 s39, s36, 0
	s_add_i32 s41, s41, 1
	s_add_u32 s10, s10, 0x80
	s_addc_u32 s11, s11, 0
	s_mul_i32 s36, s39, 0xc000
	s_mul_i32 s98, s39, 0x6000
	s_addk_i32 s98, 0xa000
	s_cmp_lg_u32 s39, 0
	s_cselect_b32 s98, s98, 0xc000
	s_lshl_b32 s98, s98, 1
	s_add_u32 s98, s98, s99
	v_mfma_f32_16x16x32_bf16 v[8:11], v[116:119], v[96:99], v[8:11]
	v_mfma_f32_16x16x32_bf16 v[4:7], v[120:123], v[96:99], v[4:7]
	v_add_u32_e32 v160, s36, v174
	v_mfma_f32_16x16x32_bf16 v[0:3], v[124:127], v[96:99], v[0:3]
	v_mfma_f32_16x16x32_bf16 v[60:63], v[80:83], v[76:79], v[60:63]
	v_add_u32_e32 v161, s36, v131
	v_mfma_f32_16x16x32_bf16 v[56:59], v[84:87], v[76:79], v[56:59]
	v_mfma_f32_16x16x32_bf16 v[52:55], v[88:91], v[76:79], v[52:55]
	v_lshl_add_u64 v[162:163], v[162:163], 0, s[14:15]
	v_mfma_f32_16x16x32_bf16 v[48:51], v[92:95], v[76:79], v[48:51]
	v_mfma_f32_16x16x32_bf16 v[44:47], v[80:83], v[72:75], v[44:47]
	v_lshl_add_u64 v[164:165], v[164:165], 0, s[14:15]
	v_mfma_f32_16x16x32_bf16 v[40:43], v[84:87], v[72:75], v[40:43]
	v_mfma_f32_16x16x32_bf16 v[36:39], v[88:91], v[72:75], v[36:39]
	v_lshl_add_u64 v[166:167], v[166:167], 0, s[14:15]
	v_mfma_f32_16x16x32_bf16 v[32:35], v[92:95], v[72:75], v[32:35]
	v_mfma_f32_16x16x32_bf16 v[28:31], v[80:83], v[68:71], v[28:31]
	v_lshl_add_u64 v[168:169], v[168:169], 0, s[14:15]
	v_mfma_f32_16x16x32_bf16 v[24:27], v[84:87], v[68:71], v[24:27]
	v_mfma_f32_16x16x32_bf16 v[20:23], v[88:91], v[68:71], v[20:23]
	v_lshl_add_u64 v[170:171], v[170:171], 0, s[14:15]
	v_mfma_f32_16x16x32_bf16 v[16:19], v[92:95], v[68:71], v[16:19]
	v_mfma_f32_16x16x32_bf16 v[12:15], v[80:83], v[64:67], v[12:15]
	v_lshl_add_u64 v[172:173], v[172:173], 0, s[14:15]
	v_mfma_f32_16x16x32_bf16 v[8:11], v[84:87], v[64:67], v[8:11]
	v_mfma_f32_16x16x32_bf16 v[4:7], v[88:91], v[64:67], v[4:7]
	v_mfma_f32_16x16x32_bf16 v[0:3], v[92:95], v[64:67], v[0:3]
	s_setprio 0
	s_barrier
	s_cmpk_eq_i32 s10, 0x800
	s_cbranch_scc0 .LBB0_109
	s_branch .LBB0_113

; #define STAGE_ALL(bufi, kt) do { STAGEA(SA(bufi, 0), brow, kt); STAGEA(SA(bufi, 1), brow + HALF, kt); STAGEB(SB(bufi), bcol, kt); } while (0)
; #define WAIT_V(n) asm volatile("s_waitcnt vmcnt(" #n ")" ::: "memory")
; #define BAR __builtin_amdgcn_s_barrier()
;     ...
;   const int wid = tid >> 6, lane = tid & 63, wr = wid >> 1, wc = wid & 1, fr = lane & 15, fq = lane >> 4;
;   acc_t acc;
; #pragma unroll
;   for (int m = 0; m < 4; ++m)
; #pragma unroll
;     for (int n = 0; n < 4; ++n) acc[m][n] = f32x4{0.f, 0.f, 0.f, 0.f};
;   const int nt = K / BK;
;   unsigned oA0, oA1, oB0, oB1;
;   { int _r, _c; stage_rc(tid * 16, _r, _c); oA0 = _r * lda + _c; oB0 = _r * ldb + _c;
;     stage_rc(tid * 16 + 8192, _r, _c); oA1 = _r * lda + _c; oB1 = _r * ldb + _c; }
;   if (!preloaded) {
;     STAGE_ALL(0, 0);
;     if (nt > 1) STAGE_ALL(1, 1);
;   }
;     ...
;     for (int t = 0; t < nt; ++t) {
;       const char* pa = (const char*)SA(b, wr >> 1);
;       const char* pb = (const char*)SB(b);
;       bf16x8 At[4][2], Bf[4][2];
; #pragma unroll
;       for (int m = 0; m < 4; ++m)
; #pragma unroll
;         for (int k = 0; k < 2; ++k) At[m][k] = *reinterpret_cast<const bf16x8*>(pa + lds_byte((wr & 1) * 64 + m * 16 + fr, k * 32 + fq * 8));
; #pragma unroll
;       for (int n = 0; n < 4; ++n)
; #pragma unroll
;         for (int k = 0; k < 2; ++k) Bf[n][k] = *reinterpret_cast<const bf16x8*>(pb + lds_byte(wc * 64 + n * 16 + fr, k * 32 + fq * 8));
;       if (t + 2 < nt) { const int b2 = (b == 0) ? 2 : b - 1; STAGE_ALL(b2, t + 2); WAIT_V(6); } else { WAIT_V(0); }
;       asm volatile("s_waitcnt lgkmcnt(0)" ::: "memory");
;       __builtin_amdgcn_sched_barrier(0);
;       BAR;
.LBB0_1020:
	s_or_b64 exec, exec, s[10:11]
	v_lshlrev_b32_e32 v4, 13, v4
	s_ashr_i32 s41, s40, 31
	s_ashr_i32 s39, s38, 31
	v_and_b32_e32 v4, 0xffffc000, v4
	v_lshlrev_b32_e32 v0, 13, v0
	v_and_b32_e32 v8, 15, v133
	v_and_b32_e32 v9, 48, v133
	s_lshl_b64 s[10:11], s[40:41], 11
	s_lshl_b64 s[36:37], s[38:39], 11
	v_lshl_add_u32 v4, v5, 10, v4
	v_and_b32_e32 v0, 0xffffc000, v0
	v_lshl_or_b32 v8, v8, 6, v9
	v_lshlrev_b32_e32 v9, 2, v133
	v_or_b32_e32 v4, v4, v6
	s_add_u32 s36, s50, s36
	v_lshl_add_u32 v0, v1, 10, v0
	v_and_b32_e32 v9, 32, v9
	v_add_u32_sdwa v196, v4, sext(v7) dst_sel:DWORD dst_unused:UNUSED_PAD src0_sel:DWORD src1_sel:WORD_0
	s_addc_u32 s37, s51, s37
	v_or_b32_e32 v0, v0, v2
	v_xad_u32 v8, v8, v9, 16
	v_lshlrev_b32_e32 v9, 6, v133
	v_lshlrev_b32_e32 v10, 7, v133
	v_lshlrev_b64 v[4:5], 1, v[196:197]
	v_add_u32_sdwa v196, v0, sext(v3) dst_sel:DWORD dst_unused:UNUSED_PAD src0_sel:DWORD src1_sel:WORD_0
	s_add_u32 s10, s54, s10
	v_and_b32_e32 v9, 0x2000, v9
	v_and_b32_e32 v10, 0x2000, v10
	v_lshlrev_b64 v[0:1], 1, v[196:197]
	s_addc_u32 s11, s55, s11
	v_mov_b32_e32 v56, 0
	v_ashrrev_i32_e32 v132, 8, v133
	v_add_u32_e32 v129, v8, v9
	v_add_u32_e32 v131, v8, v10
	v_lshl_add_u64 v[134:135], s[36:37], 0, v[4:5]
	v_lshl_add_u64 v[136:137], s[36:37], 0, v[0:1]
	v_lshl_add_u64 v[138:139], s[10:11], 0, v[4:5]
	v_lshl_add_u64 v[140:141], s[10:11], 0, v[0:1]
	s_mov_b32 s39, 0
	s_mov_b64 s[10:11], 0
	s_mov_b32 s41, 0
	v_mov_b32_e32 v57, v56
	v_mov_b32_e32 v58, v56
	v_mov_b32_e32 v59, v56
	v_mov_b32_e32 v60, v56
	v_mov_b32_e32 v61, v56
	v_mov_b32_e32 v62, v56
	v_mov_b32_e32 v63, v56
	v_mov_b32_e32 v52, v56
	v_mov_b32_e32 v53, v56
	v_mov_b32_e32 v54, v56
	v_mov_b32_e32 v55, v56
	v_mov_b32_e32 v48, v56
	v_mov_b32_e32 v49, v56
	v_mov_b32_e32 v50, v56
	v_mov_b32_e32 v51, v56
	v_mov_b32_e32 v44, v56
	v_mov_b32_e32 v45, v56
	v_mov_b32_e32 v46, v56
	v_mov_b32_e32 v47, v56
	v_mov_b32_e32 v40, v56
	v_mov_b32_e32 v41, v56
	v_mov_b32_e32 v42, v56
	v_mov_b32_e32 v43, v56
	v_mov_b32_e32 v36, v56
	v_mov_b32_e32 v37, v56
	v_mov_b32_e32 v38, v56
	v_mov_b32_e32 v39, v56
	v_mov_b32_e32 v32, v56
	v_mov_b32_e32 v33, v56
	v_mov_b32_e32 v34, v56
	v_mov_b32_e32 v35, v56
	v_mov_b32_e32 v28, v56
	v_mov_b32_e32 v29, v56
	v_mov_b32_e32 v30, v56
	v_mov_b32_e32 v31, v56
	v_mov_b32_e32 v24, v56
	v_mov_b32_e32 v25, v56
	v_mov_b32_e32 v26, v56
	v_mov_b32_e32 v27, v56
	v_mov_b32_e32 v20, v56
	v_mov_b32_e32 v21, v56
	v_mov_b32_e32 v22, v56
	v_mov_b32_e32 v23, v56
	v_mov_b32_e32 v16, v56
	v_mov_b32_e32 v17, v56
	v_mov_b32_e32 v18, v56
	v_mov_b32_e32 v19, v56
	v_mov_b32_e32 v12, v56
	v_mov_b32_e32 v13, v56
	v_mov_b32_e32 v14, v56
	v_mov_b32_e32 v15, v56
	v_mov_b32_e32 v8, v56
	v_mov_b32_e32 v9, v56
	v_mov_b32_e32 v10, v56
	v_mov_b32_e32 v11, v56
	v_mov_b32_e32 v4, v56
	v_mov_b32_e32 v5, v56
	v_mov_b32_e32 v6, v56
	v_mov_b32_e32 v7, v56
	v_mov_b32_e32 v0, v56
	v_mov_b32_e32 v1, v56
	v_mov_b32_e32 v2, v56
	v_mov_b32_e32 v3, v56
	v_readfirstlane_b32 s99, v151
	v_lshl_add_u32 v174, v132, 14, v129
	v_mov_b32_e32 v161, v131
	v_lshl_add_u64 v[162:163], v[140:141], 0, s[20:21]
	v_lshl_add_u64 v[164:165], v[138:139], 0, s[20:21]
	v_lshl_add_u64 v[166:167], v[140:141], 0, s[22:23]
	v_lshl_add_u64 v[168:169], v[138:139], 0, s[22:23]
	v_mov_b64_e32 v[170:171], v[136:137]
	v_mov_b64_e32 v[172:173], v[134:135]
	v_mov_b32_e32 v160, v174
	s_add_u32 s98, s99, 0x18000
	s_nop 0
.LBB0_1022:
	ds_read_b128 v[108:111], v160
	ds_read_b128 v[76:79], v160 offset:1024
	ds_read_b128 v[104:107], v160 offset:2048
	ds_read_b128 v[72:75], v160 offset:3072
	ds_read_b128 v[100:103], v160 offset:4096
	ds_read_b128 v[68:71], v160 offset:5120
	ds_read_b128 v[96:99], v160 offset:6144
	ds_read_b128 v[64:67], v160 offset:7168
	ds_read_b128 v[112:115], v161 offset:32768
	ds_read_b128 v[80:83], v161 offset:33792
	ds_read_b128 v[116:119], v161 offset:34816
	ds_read_b128 v[84:87], v161 offset:35840
	ds_read_b128 v[120:123], v161 offset:36864
	ds_read_b128 v[88:91], v161 offset:37888
	ds_read_b128 v[124:127], v161 offset:38912
	ds_read_b128 v[92:95], v161 offset:39936
	s_cmp_gt_u32 s41, 13
	s_cbranch_scc1 .Lgc4_nostage
	s_mov_b32 m0, s98
	s_nop 0
	global_load_lds_dwordx4 v[162:163], off
	s_add_u32 m0, s98, 0x2000
	s_nop 0
	global_load_lds_dwordx4 v[164:165], off
	s_add_u32 m0, s98, 0x4000
	s_nop 0
	global_load_lds_dwordx4 v[166:167], off
	s_waitcnt vmcnt(3)
.LBB0_1021:
	s_waitcnt lgkmcnt(0)
	s_barrier
	s_setprio 1
	s_waitcnt lgkmcnt(0)
	v_mfma_f32_16x16x32_bf16 v[56:59], v[112:115], v[108:111], v[56:59]
	v_mfma_f32_16x16x32_bf16 v[60:63], v[116:119], v[108:111], v[60:63]
	s_cmp_gt_u32 s41, 13
	s_cbranch_scc1 .Lgc4_skd3
	s_add_u32 m0, s98, 0x6000
	s_nop 0
	global_load_lds_dwordx4 v[168:169], off

; #define STAGE_ALL(bufi, kt) do { STAGEA(SA(bufi, 0), brow, kt); STAGEA(SA(bufi, 1), brow + HALF, kt); STAGEB(SB(bufi), bcol, kt); } while (0)
; #define WAIT_V(n) asm volatile("s_waitcnt vmcnt(" #n ")" ::: "memory")
; #define BAR __builtin_amdgcn_s_barrier()
;     ...
;       if (t + 2 < nt) { const int b2 = (b == 0) ? 2 : b - 1; STAGE_ALL(b2, t + 2); WAIT_V(6); } else { WAIT_V(0); }
;       asm volatile("s_waitcnt lgkmcnt(0)" ::: "memory");
;       __builtin_amdgcn_sched_barrier(0);
;       BAR;
;       __builtin_amdgcn_sched_barrier(0);
;       __builtin_amdgcn_s_setprio(1);
; #pragma unroll
;       for (int k = 0; k < 2; ++k)
; #pragma unroll
;         for (int m = 0; m < 4; ++m)
; #pragma unroll
;           for (int n = 0; n < 4; ++n) acc[m][n] = __builtin_amdgcn_mfma_f32_16x16x32_bf16(Bf[n][k], At[m][k], acc[m][n], 0, 0, 0);
;       __builtin_amdgcn_s_setprio(0);
;       __builtin_amdgcn_sched_barrier(0);
;       BAR;
;       __builtin_amdgcn_sched_barrier(0);
;       b = (b == 2) ? 0 : b + 1;
.Lgc4_skd5:
	v_mfma_f32_16x16x32_bf16 v[20:23], v[120:123], v[100:103], v[20:23]
	v_mfma_f32_16x16x32_bf16 v[16:19], v[124:127], v[100:103], v[16:19]
	v_mfma_f32_16x16x32_bf16 v[12:15], v[112:115], v[96:99], v[12:15]
	s_add_i32 s36, s39, 1
	s_cmp_lg_u32 s39, 2
	s_cselect_b32 s39, s36, 0
	s_add_i32 s41, s41, 1
	s_add_u32 s10, s10, 0x80
	s_addc_u32 s11, s11, 0
	s_mul_i32 s36, s39, 0xc000
	s_mul_i32 s98, s39, 0x6000
	s_addk_i32 s98, 0xa000
	s_cmp_lg_u32 s39, 0
	s_cselect_b32 s98, s98, 0xc000
	s_lshl_b32 s98, s98, 1
	s_add_u32 s98, s98, s99
	v_mfma_f32_16x16x32_bf16 v[8:11], v[116:119], v[96:99], v[8:11]
	v_mfma_f32_16x16x32_bf16 v[4:7], v[120:123], v[96:99], v[4:7]
	v_add_u32_e32 v160, s36, v174
	v_mfma_f32_16x16x32_bf16 v[0:3], v[124:127], v[96:99], v[0:3]
	v_mfma_f32_16x16x32_bf16 v[56:59], v[80:83], v[76:79], v[56:59]
	v_add_u32_e32 v161, s36, v131
	v_mfma_f32_16x16x32_bf16 v[60:63], v[84:87], v[76:79], v[60:63]
	v_mfma_f32_16x16x32_bf16 v[52:55], v[88:91], v[76:79], v[52:55]
	v_lshl_add_u64 v[162:163], v[162:163], 0, s[14:15]
	v_mfma_f32_16x16x32_bf16 v[48:51], v[92:95], v[76:79], v[48:51]
	v_mfma_f32_16x16x32_bf16 v[44:47], v[80:83], v[72:75], v[44:47]
	v_lshl_add_u64 v[164:165], v[164:165], 0, s[14:15]
	v_mfma_f32_16x16x32_bf16 v[40:43], v[84:87], v[72:75], v[40:43]
	v_mfma_f32_16x16x32_bf16 v[36:39], v[88:91], v[72:75], v[36:39]
	v_lshl_add_u64 v[166:167], v[166:167], 0, s[14:15]
	v_mfma_f32_16x16x32_bf16 v[32:35], v[92:95], v[72:75], v[32:35]
	v_mfma_f32_16x16x32_bf16 v[28:31], v[80:83], v[68:71], v[28:31]
	v_lshl_add_u64 v[168:169], v[168:169], 0, s[14:15]
	v_mfma_f32_16x16x32_bf16 v[24:27], v[84:87], v[68:71], v[24:27]
	v_mfma_f32_16x16x32_bf16 v[20:23], v[88:91], v[68:71], v[20:23]
	v_lshl_add_u64 v[170:171], v[170:171], 0, s[14:15]
	v_mfma_f32_16x16x32_bf16 v[16:19], v[92:95], v[68:71], v[16:19]
	v_mfma_f32_16x16x32_bf16 v[12:15], v[80:83], v[64:67], v[12:15]
	v_lshl_add_u64 v[172:173], v[172:173], 0, s[14:15]
	v_mfma_f32_16x16x32_bf16 v[8:11], v[84:87], v[64:67], v[8:11]
	v_mfma_f32_16x16x32_bf16 v[4:7], v[88:91], v[64:67], v[4:7]
	v_mfma_f32_16x16x32_bf16 v[0:3], v[92:95], v[64:67], v[0:3]
	s_setprio 0
	s_barrier
	s_cmpk_eq_i32 s10, 0x800
	s_cbranch_scc0 .LBB0_1022
	s_branch .LBB0_1026

; #define STAGE_ALL(bufi, kt) do { STAGEA(SA(bufi, 0), brow, kt); STAGEA(SA(bufi, 1), brow + HALF, kt); STAGEB(SB(bufi), bcol, kt); } while (0)
; #define WAIT_V(n) asm volatile("s_waitcnt vmcnt(" #n ")" ::: "memory")
; #define BAR __builtin_amdgcn_s_barrier()
;     ...
;   const int wid = tid >> 6, lane = tid & 63, wr = wid >> 1, wc = wid & 1, fr = lane & 15, fq = lane >> 4;
;   acc_t acc;
; #pragma unroll
;   for (int m = 0; m < 4; ++m)
; #pragma unroll
;     for (int n = 0; n < 4; ++n) acc[m][n] = f32x4{0.f, 0.f, 0.f, 0.f};
;   const int nt = K / BK;
;   unsigned oA0, oA1, oB0, oB1;
;   { int _r, _c; stage_rc(tid * 16, _r, _c); oA0 = _r * lda + _c; oB0 = _r * ldb + _c;
;     stage_rc(tid * 16 + 8192, _r, _c); oA1 = _r * lda + _c; oB1 = _r * ldb + _c; }
;   if (!preloaded) {
;     STAGE_ALL(0, 0);
;     if (nt > 1) STAGE_ALL(1, 1);
;   }
;     ...
;     for (int t = 0; t < nt; ++t) {
;       const char* pa = (const char*)SA(b, wr >> 1);
;       const char* pb = (const char*)SB(b);
;       bf16x8 At[4][2], Bf[4][2];
; #pragma unroll
;       for (int m = 0; m < 4; ++m)
; #pragma unroll
;         for (int k = 0; k < 2; ++k) At[m][k] = *reinterpret_cast<const bf16x8*>(pa + lds_byte((wr & 1) * 64 + m * 16 + fr, k * 32 + fq * 8));
; #pragma unroll
;       for (int n = 0; n < 4; ++n)
; #pragma unroll
;         for (int k = 0; k < 2; ++k) Bf[n][k] = *reinterpret_cast<const bf16x8*>(pb + lds_byte(wc * 64 + n * 16 + fr, k * 32 + fq * 8));
;       if (t + 2 < nt) { const int b2 = (b == 0) ? 2 : b - 1; STAGE_ALL(b2, t + 2); WAIT_V(6); } else { WAIT_V(0); }
;       asm volatile("s_waitcnt lgkmcnt(0)" ::: "memory");
;       __builtin_amdgcn_sched_barrier(0);
;       BAR;
.LBB0_1056:
	s_or_b64 exec, exec, s[10:11]
	v_and_b32_e32 v8, 15, v133
	v_and_b32_e32 v9, 48, v133
	v_lshl_or_b32 v8, v8, 6, v9
	v_lshlrev_b32_e32 v9, 2, v133
	v_and_b32_e32 v9, 32, v9
	v_xad_u32 v8, v8, v9, 16
	v_lshlrev_b32_e32 v9, 6, v133
	v_lshlrev_b32_e32 v10, 7, v133
	v_and_b32_e32 v9, 0x2000, v9
	v_and_b32_e32 v10, 0x2000, v10
	s_movk_i32 s60, 0xb00
	v_add_u32_e32 v129, v8, v9
	v_add_u32_e32 v131, v8, v10
	v_lshrrev_b32_e32 v8, 1, v4
	v_mul_lo_u32 v4, v6, s60
	s_mov_b32 s61, 0xb000
	v_mad_u64_u32 v[8:9], s[10:11], v8, s61, v[4:5]
	v_or_b32_e32 v4, v8, v5
	s_add_u32 s10, s46, s41
	v_lshrrev_b32_e32 v6, 1, v0
	v_mul_lo_u32 v0, v2, s60
	v_add_u32_sdwa v196, v4, sext(v7) dst_sel:DWORD dst_unused:UNUSED_PAD src0_sel:DWORD src1_sel:WORD_0
	s_addc_u32 s11, s47, s40
	v_mad_u64_u32 v[6:7], s[40:41], v6, s61, v[0:1]
	v_or_b32_e32 v0, v6, v1
	v_lshlrev_b64 v[4:5], 1, v[196:197]
	v_add_u32_sdwa v196, v0, sext(v3) dst_sel:DWORD dst_unused:UNUSED_PAD src0_sel:DWORD src1_sel:WORD_0
	v_lshlrev_b64 v[0:1], 1, v[196:197]
	v_lshl_add_u64 v[134:135], s[10:11], 0, v[4:5]
	v_lshl_add_u64 v[136:137], s[10:11], 0, v[0:1]
	s_add_u32 s10, s54, s37
	s_addc_u32 s11, s55, s36
	v_mov_b32_e32 v60, 0
	v_ashrrev_i32_e32 v132, 8, v133
	v_lshl_add_u64 v[138:139], s[10:11], 0, v[4:5]
	v_lshl_add_u64 v[140:141], s[10:11], 0, v[0:1]
	s_mov_b32 s60, 0
	s_mov_b64 s[10:11], 0
	s_mov_b32 s61, 0
	v_mov_b32_e32 v61, v60
	v_mov_b32_e32 v62, v60
	v_mov_b32_e32 v63, v60
	v_mov_b32_e32 v56, v60
	v_mov_b32_e32 v57, v60
	v_mov_b32_e32 v58, v60
	v_mov_b32_e32 v59, v60
	v_mov_b32_e32 v52, v60
	v_mov_b32_e32 v53, v60
	v_mov_b32_e32 v54, v60
	v_mov_b32_e32 v55, v60
	v_mov_b32_e32 v48, v60
	v_mov_b32_e32 v49, v60
	v_mov_b32_e32 v50, v60
	v_mov_b32_e32 v51, v60
	v_mov_b32_e32 v44, v60
	v_mov_b32_e32 v45, v60
	v_mov_b32_e32 v46, v60
	v_mov_b32_e32 v47, v60
	v_mov_b32_e32 v40, v60
	v_mov_b32_e32 v41, v60
	v_mov_b32_e32 v42, v60
	v_mov_b32_e32 v43, v60
	v_mov_b32_e32 v36, v60
	v_mov_b32_e32 v37, v60
	v_mov_b32_e32 v38, v60
	v_mov_b32_e32 v39, v60
	v_mov_b32_e32 v32, v60
	v_mov_b32_e32 v33, v60
	v_mov_b32_e32 v34, v60
	v_mov_b32_e32 v35, v60
	v_mov_b32_e32 v28, v60
	v_mov_b32_e32 v29, v60
	v_mov_b32_e32 v30, v60
	v_mov_b32_e32 v31, v60
	v_mov_b32_e32 v24, v60
	v_mov_b32_e32 v25, v60
	v_mov_b32_e32 v26, v60
	v_mov_b32_e32 v27, v60
	v_mov_b32_e32 v20, v60
	v_mov_b32_e32 v21, v60
	v_mov_b32_e32 v22, v60
	v_mov_b32_e32 v23, v60
	v_mov_b32_e32 v16, v60
	v_mov_b32_e32 v17, v60
	v_mov_b32_e32 v18, v60
	v_mov_b32_e32 v19, v60
	v_mov_b32_e32 v12, v60
	v_mov_b32_e32 v13, v60
	v_mov_b32_e32 v14, v60
	v_mov_b32_e32 v15, v60
	v_mov_b32_e32 v8, v60
	v_mov_b32_e32 v9, v60
	v_mov_b32_e32 v10, v60
	v_mov_b32_e32 v11, v60
	v_mov_b32_e32 v4, v60
	v_mov_b32_e32 v5, v60
	v_mov_b32_e32 v6, v60
	v_mov_b32_e32 v7, v60
	v_mov_b32_e32 v0, v60
	v_mov_b32_e32 v1, v60
	v_mov_b32_e32 v2, v60
	v_mov_b32_e32 v3, v60
	v_readfirstlane_b32 s99, v151
	v_lshl_add_u32 v174, v132, 14, v129
	v_mov_b32_e32 v161, v131
	v_lshl_add_u64 v[162:163], v[140:141], 0, s[16:17]
	v_lshl_add_u64 v[164:165], v[138:139], 0, s[16:17]
	v_lshl_add_u64 v[166:167], v[140:141], 0, s[18:19]
	v_lshl_add_u64 v[168:169], v[138:139], 0, s[18:19]
	v_mov_b64_e32 v[170:171], v[136:137]
	v_mov_b64_e32 v[172:173], v[134:135]
	v_mov_b32_e32 v160, v174
	s_add_u32 s98, s99, 0x18000
	s_nop 0
.LBB0_1058:
	ds_read_b128 v[108:111], v160
	ds_read_b128 v[76:79], v160 offset:1024
	ds_read_b128 v[104:107], v160 offset:2048
	ds_read_b128 v[72:75], v160 offset:3072
	ds_read_b128 v[100:103], v160 offset:4096
	ds_read_b128 v[68:71], v160 offset:5120
	ds_read_b128 v[96:99], v160 offset:6144
	ds_read_b128 v[64:67], v160 offset:7168
	ds_read_b128 v[112:115], v161 offset:32768
	ds_read_b128 v[80:83], v161 offset:33792
	ds_read_b128 v[116:119], v161 offset:34816
	ds_read_b128 v[84:87], v161 offset:35840
	ds_read_b128 v[120:123], v161 offset:36864
	ds_read_b128 v[88:91], v161 offset:37888
	ds_read_b128 v[124:127], v161 offset:38912
	ds_read_b128 v[92:95], v161 offset:39936
	s_cmp_gt_u32 s61, 41
	s_cbranch_scc1 .Lgc5_nostage
	s_mov_b32 m0, s98
	s_nop 0
	global_load_lds_dwordx4 v[162:163], off
	s_add_u32 m0, s98, 0x2000
	s_nop 0
	global_load_lds_dwordx4 v[164:165], off
	s_add_u32 m0, s98, 0x4000
	s_nop 0
	global_load_lds_dwordx4 v[166:167], off
	s_waitcnt vmcnt(3)
.LBB0_1057:
	s_waitcnt lgkmcnt(0)
	s_barrier
	s_setprio 1
	s_waitcnt lgkmcnt(0)
	v_mfma_f32_16x16x32_bf16 v[60:63], v[112:115], v[108:111], v[60:63]
	v_mfma_f32_16x16x32_bf16 v[56:59], v[116:119], v[108:111], v[56:59]
	s_cmp_gt_u32 s61, 41
	s_cbranch_scc1 .Lgc5_skd3
	s_add_u32 m0, s98, 0x6000
	s_nop 0
	global_load_lds_dwordx4 v[168:169], off

; #define STAGE_ALL(bufi, kt) do { STAGEA(SA(bufi, 0), brow, kt); STAGEA(SA(bufi, 1), brow + HALF, kt); STAGEB(SB(bufi), bcol, kt); } while (0)
; #define WAIT_V(n) asm volatile("s_waitcnt vmcnt(" #n ")" ::: "memory")
; #define BAR __builtin_amdgcn_s_barrier()
;     ...
;       if (t + 2 < nt) { const int b2 = (b == 0) ? 2 : b - 1; STAGE_ALL(b2, t + 2); WAIT_V(6); } else { WAIT_V(0); }
;       asm volatile("s_waitcnt lgkmcnt(0)" ::: "memory");
;       __builtin_amdgcn_sched_barrier(0);
;       BAR;
;       __builtin_amdgcn_sched_barrier(0);
;       __builtin_amdgcn_s_setprio(1);
; #pragma unroll
;       for (int k = 0; k < 2; ++k)
; #pragma unroll
;         for (int m = 0; m < 4; ++m)
; #pragma unroll
;           for (int n = 0; n < 4; ++n) acc[m][n] = __builtin_amdgcn_mfma_f32_16x16x32_bf16(Bf[n][k], At[m][k], acc[m][n], 0, 0, 0);
;       __builtin_amdgcn_s_setprio(0);
;       __builtin_amdgcn_sched_barrier(0);
;       BAR;
;       __builtin_amdgcn_sched_barrier(0);
;       b = (b == 2) ? 0 : b + 1;
.Lgc5_skd5:
	v_mfma_f32_16x16x32_bf16 v[20:23], v[120:123], v[100:103], v[20:23]
	v_mfma_f32_16x16x32_bf16 v[16:19], v[124:127], v[100:103], v[16:19]
	v_mfma_f32_16x16x32_bf16 v[12:15], v[112:115], v[96:99], v[12:15]
	s_add_i32 s36, s60, 1
	s_cmp_lg_u32 s60, 2
	s_cselect_b32 s60, s36, 0
	s_add_i32 s61, s61, 1
	s_add_u32 s10, s10, 0x80
	s_addc_u32 s11, s11, 0
	s_mul_i32 s36, s60, 0xc000
	s_mul_i32 s98, s60, 0x6000
	s_addk_i32 s98, 0xa000
	s_cmp_lg_u32 s60, 0
	s_cselect_b32 s98, s98, 0xc000
	s_lshl_b32 s98, s98, 1
	s_add_u32 s98, s98, s99
	v_mfma_f32_16x16x32_bf16 v[8:11], v[116:119], v[96:99], v[8:11]
	v_mfma_f32_16x16x32_bf16 v[4:7], v[120:123], v[96:99], v[4:7]
	v_add_u32_e32 v160, s36, v174
	v_mfma_f32_16x16x32_bf16 v[0:3], v[124:127], v[96:99], v[0:3]
	v_mfma_f32_16x16x32_bf16 v[60:63], v[80:83], v[76:79], v[60:63]
	v_add_u32_e32 v161, s36, v131
	v_mfma_f32_16x16x32_bf16 v[56:59], v[84:87], v[76:79], v[56:59]
	v_mfma_f32_16x16x32_bf16 v[52:55], v[88:91], v[76:79], v[52:55]
	v_lshl_add_u64 v[162:163], v[162:163], 0, s[14:15]
	v_mfma_f32_16x16x32_bf16 v[48:51], v[92:95], v[76:79], v[48:51]
	v_mfma_f32_16x16x32_bf16 v[44:47], v[80:83], v[72:75], v[44:47]
	v_lshl_add_u64 v[164:165], v[164:165], 0, s[14:15]
	v_mfma_f32_16x16x32_bf16 v[40:43], v[84:87], v[72:75], v[40:43]
	v_mfma_f32_16x16x32_bf16 v[36:39], v[88:91], v[72:75], v[36:39]
	v_lshl_add_u64 v[166:167], v[166:167], 0, s[14:15]
	v_mfma_f32_16x16x32_bf16 v[32:35], v[92:95], v[72:75], v[32:35]
	v_mfma_f32_16x16x32_bf16 v[28:31], v[80:83], v[68:71], v[28:31]
	v_lshl_add_u64 v[168:169], v[168:169], 0, s[14:15]
	v_mfma_f32_16x16x32_bf16 v[24:27], v[84:87], v[68:71], v[24:27]
	v_mfma_f32_16x16x32_bf16 v[20:23], v[88:91], v[68:71], v[20:23]
	v_lshl_add_u64 v[170:171], v[170:171], 0, s[14:15]
	v_mfma_f32_16x16x32_bf16 v[16:19], v[92:95], v[68:71], v[16:19]
	v_mfma_f32_16x16x32_bf16 v[12:15], v[80:83], v[64:67], v[12:15]
	v_lshl_add_u64 v[172:173], v[172:173], 0, s[14:15]
	v_mfma_f32_16x16x32_bf16 v[8:11], v[84:87], v[64:67], v[8:11]
	v_mfma_f32_16x16x32_bf16 v[4:7], v[88:91], v[64:67], v[4:7]
	v_mfma_f32_16x16x32_bf16 v[0:3], v[92:95], v[64:67], v[0:3]
	s_setprio 0
	s_barrier
	s_cmpk_eq_i32 s10, 0x1600
	s_cbranch_scc0 .LBB0_1058
	s_branch .LBB0_1062

; #define STAGE_ALL(bufi, kt) do { STAGEA(SA(bufi, 0), brow, kt); STAGEA(SA(bufi, 1), brow + HALF, kt); STAGEB(SB(bufi), bcol, kt); } while (0)
; #define WAIT_V(n) asm volatile("s_waitcnt vmcnt(" #n ")" ::: "memory")
; #define BAR __builtin_amdgcn_s_barrier()
;     ...
;   const int wid = tid >> 6, lane = tid & 63, wr = wid >> 1, wc = wid & 1, fr = lane & 15, fq = lane >> 4;
;   acc_t acc;
; #pragma unroll
;   for (int m = 0; m < 4; ++m)
; #pragma unroll
;     for (int n = 0; n < 4; ++n) acc[m][n] = f32x4{0.f, 0.f, 0.f, 0.f};
;   const int nt = K / BK;
;   unsigned oA0, oA1, oB0, oB1;
;   { int _r, _c; stage_rc(tid * 16, _r, _c); oA0 = _r * lda + _c; oB0 = _r * ldb + _c;
;     stage_rc(tid * 16 + 8192, _r, _c); oA1 = _r * lda + _c; oB1 = _r * ldb + _c; }
;   if (!preloaded) {
;     STAGE_ALL(0, 0);
;     if (nt > 1) STAGE_ALL(1, 1);
;   }
;     ...
;     for (int t = 0; t < nt; ++t) {
;       const char* pa = (const char*)SA(b, wr >> 1);
;       const char* pb = (const char*)SB(b);
;       bf16x8 At[4][2], Bf[4][2];
; #pragma unroll
;       for (int m = 0; m < 4; ++m)
; #pragma unroll
;         for (int k = 0; k < 2; ++k) At[m][k] = *reinterpret_cast<const bf16x8*>(pa + lds_byte((wr & 1) * 64 + m * 16 + fr, k * 32 + fq * 8));
; #pragma unroll
;       for (int n = 0; n < 4; ++n)
; #pragma unroll
;         for (int k = 0; k < 2; ++k) Bf[n][k] = *reinterpret_cast<const bf16x8*>(pb + lds_byte(wc * 64 + n * 16 + fr, k * 32 + fq * 8));
;       if (t + 2 < nt) { const int b2 = (b == 0) ? 2 : b - 1; STAGE_ALL(b2, t + 2); WAIT_V(6); } else { WAIT_V(0); }
;       asm volatile("s_waitcnt lgkmcnt(0)" ::: "memory");
;       __builtin_amdgcn_sched_barrier(0);
;       BAR;
.LBB0_1264:
	s_or_b64 exec, exec, s[44:45]
	v_lshlrev_b32_e32 v4, 13, v4
	v_and_b32_e32 v4, 0xffffc000, v4
	v_lshlrev_b32_e32 v0, 13, v0
	v_lshl_add_u32 v4, v5, 10, v4
	v_and_b32_e32 v0, 0xffffc000, v0
	s_ashr_i32 s43, s42, 31
	s_ashr_i32 s11, s10, 31
	v_or_b32_e32 v4, v4, v6
	v_lshl_add_u32 v0, v1, 10, v0
	v_and_b32_e32 v8, 15, v141
	v_and_b32_e32 v9, 48, v141
	s_lshl_b64 s[36:37], s[42:43], 11
	s_lshl_b64 s[10:11], s[10:11], 11
	v_add_u32_sdwa v196, v4, sext(v7) dst_sel:DWORD dst_unused:UNUSED_PAD src0_sel:DWORD src1_sel:WORD_0
	v_or_b32_e32 v0, v0, v2
	v_lshl_or_b32 v8, v8, 6, v9
	v_lshlrev_b32_e32 v9, 2, v141
	v_lshlrev_b64 v[4:5], 1, v[196:197]
	s_add_u32 s10, s48, s10
	v_add_u32_sdwa v196, v0, sext(v3) dst_sel:DWORD dst_unused:UNUSED_PAD src0_sel:DWORD src1_sel:WORD_0
	v_and_b32_e32 v9, 32, v9
	s_addc_u32 s11, s49, s11
	v_lshlrev_b64 v[0:1], 1, v[196:197]
	v_xad_u32 v8, v8, v9, 16
	v_lshlrev_b32_e32 v9, 6, v141
	v_lshlrev_b32_e32 v10, 7, v141
	v_lshl_add_u64 v[132:133], s[10:11], 0, v[4:5]
	v_lshl_add_u64 v[134:135], s[10:11], 0, v[0:1]
	s_add_u32 s10, s54, s36
	v_and_b32_e32 v9, 0x2000, v9
	v_and_b32_e32 v10, 0x2000, v10
	s_addc_u32 s11, s55, s37
	v_mov_b32_e32 v56, 0
	v_add_u32_e32 v129, v8, v9
	v_add_u32_e32 v131, v8, v10
	v_lshl_add_u64 v[136:137], s[10:11], 0, v[4:5]
	v_lshl_add_u64 v[138:139], s[10:11], 0, v[0:1]
	s_mov_b32 s43, 0
	s_mov_b64 s[10:11], 0
	s_mov_b32 s58, 0
	v_mov_b32_e32 v57, v56
	v_mov_b32_e32 v58, v56
	v_mov_b32_e32 v59, v56
	v_mov_b32_e32 v48, v56
	v_mov_b32_e32 v49, v56
	v_mov_b32_e32 v50, v56
	v_mov_b32_e32 v51, v56
	v_mov_b32_e32 v60, v56
	v_mov_b32_e32 v61, v56
	v_mov_b32_e32 v62, v56
	v_mov_b32_e32 v63, v56
	v_mov_b32_e32 v52, v56
	v_mov_b32_e32 v53, v56
	v_mov_b32_e32 v54, v56
	v_mov_b32_e32 v55, v56
	v_mov_b32_e32 v40, v56
	v_mov_b32_e32 v41, v56
	v_mov_b32_e32 v42, v56
	v_mov_b32_e32 v43, v56
	v_mov_b32_e32 v32, v56
	v_mov_b32_e32 v33, v56
	v_mov_b32_e32 v34, v56
	v_mov_b32_e32 v35, v56
	v_mov_b32_e32 v44, v56
	v_mov_b32_e32 v45, v56
	v_mov_b32_e32 v46, v56
	v_mov_b32_e32 v47, v56
	v_mov_b32_e32 v36, v56
	v_mov_b32_e32 v37, v56
	v_mov_b32_e32 v38, v56
	v_mov_b32_e32 v39, v56
	v_mov_b32_e32 v24, v56
	v_mov_b32_e32 v25, v56
	v_mov_b32_e32 v26, v56
	v_mov_b32_e32 v27, v56
	v_mov_b32_e32 v16, v56
	v_mov_b32_e32 v17, v56
	v_mov_b32_e32 v18, v56
	v_mov_b32_e32 v19, v56
	v_mov_b32_e32 v28, v56
	v_mov_b32_e32 v29, v56
	v_mov_b32_e32 v30, v56
	v_mov_b32_e32 v31, v56
	v_mov_b32_e32 v20, v56
	v_mov_b32_e32 v21, v56
	v_mov_b32_e32 v22, v56
	v_mov_b32_e32 v23, v56
	v_mov_b32_e32 v8, v56
	v_mov_b32_e32 v9, v56
	v_mov_b32_e32 v10, v56
	v_mov_b32_e32 v11, v56
	v_mov_b32_e32 v0, v56
	v_mov_b32_e32 v1, v56
	v_mov_b32_e32 v2, v56
	v_mov_b32_e32 v3, v56
	v_mov_b32_e32 v12, v56
	v_mov_b32_e32 v13, v56
	v_mov_b32_e32 v14, v56
	v_mov_b32_e32 v15, v56
	v_mov_b32_e32 v4, v56
	v_mov_b32_e32 v5, v56
	v_mov_b32_e32 v6, v56
	v_mov_b32_e32 v7, v56
	v_ashrrev_i32_e32 v140, 8, v141
	v_readfirstlane_b32 s99, v151
	v_lshl_add_u32 v174, v140, 14, v129
	v_mov_b32_e32 v161, v131
	v_lshl_add_u64 v[162:163], v[138:139], 0, s[20:21]
	v_lshl_add_u64 v[164:165], v[136:137], 0, s[20:21]
	v_lshl_add_u64 v[166:167], v[138:139], 0, s[22:23]
	v_lshl_add_u64 v[168:169], v[136:137], 0, s[22:23]
	v_mov_b64_e32 v[170:171], v[134:135]
	v_mov_b64_e32 v[172:173], v[132:133]
	v_mov_b32_e32 v160, v174
	s_add_u32 s98, s99, 0x18000
	s_nop 0
.LBB0_1266:
	ds_read_b128 v[108:111], v160
	ds_read_b128 v[76:79], v160 offset:1024
	ds_read_b128 v[104:107], v160 offset:2048
	ds_read_b128 v[72:75], v160 offset:3072
	ds_read_b128 v[100:103], v160 offset:4096
	ds_read_b128 v[68:71], v160 offset:5120
	ds_read_b128 v[96:99], v160 offset:6144
	ds_read_b128 v[64:67], v160 offset:7168
	ds_read_b128 v[112:115], v161 offset:32768
	ds_read_b128 v[80:83], v161 offset:33792
	ds_read_b128 v[116:119], v161 offset:34816
	ds_read_b128 v[84:87], v161 offset:35840
	ds_read_b128 v[120:123], v161 offset:36864
	ds_read_b128 v[88:91], v161 offset:37888
	ds_read_b128 v[124:127], v161 offset:38912
	ds_read_b128 v[92:95], v161 offset:39936
	s_cmp_gt_u32 s58, 13
	s_cbranch_scc1 .Lgc6_nostage
	s_mov_b32 m0, s98
	s_nop 0
	global_load_lds_dwordx4 v[162:163], off
	s_add_u32 m0, s98, 0x2000
	s_nop 0
	global_load_lds_dwordx4 v[164:165], off
	s_add_u32 m0, s98, 0x4000
	s_nop 0
	global_load_lds_dwordx4 v[166:167], off
	s_waitcnt vmcnt(3)
.LBB0_1265:
	s_waitcnt lgkmcnt(0)
	s_barrier
	s_setprio 1
	s_waitcnt lgkmcnt(0)
	v_mfma_f32_16x16x32_bf16 v[56:59], v[112:115], v[108:111], v[56:59]
	v_mfma_f32_16x16x32_bf16 v[48:51], v[116:119], v[108:111], v[48:51]
	s_cmp_gt_u32 s58, 13
	s_cbranch_scc1 .Lgc6_skd3
	s_add_u32 m0, s98, 0x6000
	s_nop 0
	global_load_lds_dwordx4 v[168:169], off

; #define STAGE_ALL(bufi, kt) do { STAGEA(SA(bufi, 0), brow, kt); STAGEA(SA(bufi, 1), brow + HALF, kt); STAGEB(SB(bufi), bcol, kt); } while (0)
; #define WAIT_V(n) asm volatile("s_waitcnt vmcnt(" #n ")" ::: "memory")
; #define BAR __builtin_amdgcn_s_barrier()
;     ...
;       if (t + 2 < nt) { const int b2 = (b == 0) ? 2 : b - 1; STAGE_ALL(b2, t + 2); WAIT_V(6); } else { WAIT_V(0); }
;       asm volatile("s_waitcnt lgkmcnt(0)" ::: "memory");
;       __builtin_amdgcn_sched_barrier(0);
;       BAR;
;       __builtin_amdgcn_sched_barrier(0);
;       __builtin_amdgcn_s_setprio(1);
; #pragma unroll
;       for (int k = 0; k < 2; ++k)
; #pragma unroll
;         for (int m = 0; m < 4; ++m)
; #pragma unroll
;           for (int n = 0; n < 4; ++n) acc[m][n] = __builtin_amdgcn_mfma_f32_16x16x32_bf16(Bf[n][k], At[m][k], acc[m][n], 0, 0, 0);
;       __builtin_amdgcn_s_setprio(0);
;       __builtin_amdgcn_sched_barrier(0);
;       BAR;
;       __builtin_amdgcn_sched_barrier(0);
;       b = (b == 2) ? 0 : b + 1;
.Lgc6_skd5:
	v_mfma_f32_16x16x32_bf16 v[28:31], v[120:123], v[100:103], v[28:31]
	v_mfma_f32_16x16x32_bf16 v[20:23], v[124:127], v[100:103], v[20:23]
	v_mfma_f32_16x16x32_bf16 v[8:11], v[112:115], v[96:99], v[8:11]
	s_add_i32 s36, s43, 1
	s_cmp_lg_u32 s43, 2
	s_cselect_b32 s43, s36, 0
	s_add_i32 s58, s58, 1
	s_add_u32 s10, s10, 0x80
	s_addc_u32 s11, s11, 0
	s_mul_i32 s36, s43, 0xc000
	s_mul_i32 s98, s43, 0x6000
	s_addk_i32 s98, 0xa000
	s_cmp_lg_u32 s43, 0
	s_cselect_b32 s98, s98, 0xc000
	s_lshl_b32 s98, s98, 1
	s_add_u32 s98, s98, s99
	v_mfma_f32_16x16x32_bf16 v[0:3], v[116:119], v[96:99], v[0:3]
	v_mfma_f32_16x16x32_bf16 v[12:15], v[120:123], v[96:99], v[12:15]
	v_add_u32_e32 v160, s36, v174
	v_mfma_f32_16x16x32_bf16 v[4:7], v[124:127], v[96:99], v[4:7]
	v_mfma_f32_16x16x32_bf16 v[56:59], v[80:83], v[76:79], v[56:59]
	v_add_u32_e32 v161, s36, v131
	v_mfma_f32_16x16x32_bf16 v[48:51], v[84:87], v[76:79], v[48:51]
	v_mfma_f32_16x16x32_bf16 v[60:63], v[88:91], v[76:79], v[60:63]
	v_lshl_add_u64 v[162:163], v[162:163], 0, s[14:15]
	v_mfma_f32_16x16x32_bf16 v[52:55], v[92:95], v[76:79], v[52:55]
	v_mfma_f32_16x16x32_bf16 v[40:43], v[80:83], v[72:75], v[40:43]
	v_lshl_add_u64 v[164:165], v[164:165], 0, s[14:15]
	v_mfma_f32_16x16x32_bf16 v[32:35], v[84:87], v[72:75], v[32:35]
	v_mfma_f32_16x16x32_bf16 v[44:47], v[88:91], v[72:75], v[44:47]
	v_lshl_add_u64 v[166:167], v[166:167], 0, s[14:15]
	v_mfma_f32_16x16x32_bf16 v[36:39], v[92:95], v[72:75], v[36:39]
	v_mfma_f32_16x16x32_bf16 v[24:27], v[80:83], v[68:71], v[24:27]
	v_lshl_add_u64 v[168:169], v[168:169], 0, s[14:15]
	v_mfma_f32_16x16x32_bf16 v[16:19], v[84:87], v[68:71], v[16:19]
	v_mfma_f32_16x16x32_bf16 v[28:31], v[88:91], v[68:71], v[28:31]
	v_lshl_add_u64 v[170:171], v[170:171], 0, s[14:15]
	v_mfma_f32_16x16x32_bf16 v[20:23], v[92:95], v[68:71], v[20:23]
	v_mfma_f32_16x16x32_bf16 v[8:11], v[80:83], v[64:67], v[8:11]
	v_lshl_add_u64 v[172:173], v[172:173], 0, s[14:15]
	v_mfma_f32_16x16x32_bf16 v[0:3], v[84:87], v[64:67], v[0:3]
	v_mfma_f32_16x16x32_bf16 v[12:15], v[88:91], v[64:67], v[12:15]
	v_mfma_f32_16x16x32_bf16 v[4:7], v[92:95], v[64:67], v[4:7]
	s_setprio 0
	s_barrier
	s_cmpk_eq_i32 s10, 0x800
	s_cbranch_scc0 .LBB0_1266
	s_branch .LBB0_1270
